# PN: removed the 16 fallback register copies at the row-loop top (they only mattered when no next row exists)
# baseline (speedup 1.0000x reference)
; DI void phase_norm(const Params& p, int l, const float* xin, LAS unsigned char* lds, int G, int bid) {
;     ...
;     for (int row = gw; row < M; row += NGW) {
;         const int b = row / S;
;         f32x4 v[4]; float ss = 0.f;
; #pragma unroll
;         for (int j = 0; j < 4; ++j) v[j] = vn[j];
;         if (row + NGW < M) {
; #pragma unroll
;             for (int j = 0; j < 4; ++j) vn[j] = ((const f32x4*)(xin + (size_t)(row + NGW) * D) + lane)[64 * j]; }
.LBB0_140:
	v_add_u32_e32 v179, s10, v178
	s_mov_b32 s0, 0x8000
	v_cmp_gt_i32_e32 vcc, s0, v179
	s_movk_i32 s0, 0x7fff
	v_cmp_lt_i32_e64 s[42:43], s0, v179
	s_waitcnt vmcnt(15)
	s_waitcnt vmcnt(14)
	s_waitcnt vmcnt(13)
	s_waitcnt vmcnt(12)
	s_and_saveexec_b64 s[0:1], vcc
	s_cbranch_execz .LBB0_142
	global_load_dwordx4 v[130:133], v[174:175], off
	global_load_dwordx4 v[134:137], v[174:175], off offset:1024
	global_load_dwordx4 v[138:141], v[174:175], off offset:2048
	global_load_dwordx4 v[142:145], v[174:175], off offset:3072
